# attention unit prologue: q_norm gain loads batched ahead with counted waits (was 8 exposed round trips)
# baseline (speedup 1.0000x reference)
; __device__ __forceinline__ float bf_lo(unsigned w) { return __uint_as_float(w << 16); }
; __device__ __forceinline__ float bf_hi(unsigned w) { return __uint_as_float(w & 0xffff0000u); }
; __device__ __forceinline__ void attn_unit_dma(const bf16_t* __restrict__ Qb, const bf16_t* __restrict__ Kh, const bf16_t* __restrict__ Vh, int seq, char* lds, LAS unsigned char* ldsl, ...
;     ...
;   const bf16_t* Qw = Qb + (long)(wid * QBLK + r32) * LDQ + hi * 8;
; #pragma unroll
;   for (int d0 = 0; d0 < 12; ++d0) qr[d0] = *reinterpret_cast<const bf16x8*>(Qw + d0 * 16);
;   {
;     float ss = 0.f;
; #pragma unroll
;     for (int d0 = 0; d0 < 12; ++d0) { const u32x4 w = *reinterpret_cast<const u32x4*>(&qr[d0]); float f[8]; f[0] = bf_lo(w.x); f[1] = bf_hi(w.x); f[2] = bf_lo(w.y); f[3] = bf_hi(w.y); f[4] = bf_lo(w.z); f[5] = bf_hi(w.z); f[6] = bf_lo(w.w); f[7] = bf_hi(w.w);
; #pragma unroll
;       for (int e = 0; e < 8; ++e) ss += f[e] * f[e]; }
;     { auto rr_ = __builtin_amdgcn_permlane32_swap(__float_as_uint(ss), __float_as_uint(ss), false, false); ss = __uint_as_float(rr_[0]) + __uint_as_float(rr_[1]); }
.LBB0_819:
	s_mul_i32 s7, s21, 0x1800
	s_mul_hi_u32 s10, s20, 0x1800
	s_and_b32 s36, s25, 15
	s_add_i32 s10, s10, s7
	s_mul_i32 s7, s20, 0x1800
	s_add_u32 s7, s39, s7
	s_addc_u32 s11, s40, s10
	s_mul_i32 s10, s36, 0xc0
	s_lshl_b32 s26, s10, 1
	v_mov_b32_e32 v34, v0
	s_add_u32 s10, s7, s26
	s_addc_u32 s11, s11, 0
	v_readfirstlane_b32 s63, v34
	s_ashr_i32 s24, s63, 6
	v_and_b32_e32 v180, 31, v34
	s_lshl_b32 s7, s24, 5
	v_bfe_u32 v35, v34, 5, 1
	v_or_b32_e32 v4, s7, v180
	v_mov_b64_e32 v[2:3], s[10:11]
	v_mad_i64_i32 v[2:3], s[10:11], v4, s53, v[2:3]
	v_lshlrev_b32_e32 v114, 4, v35
	v_lshl_add_u64 v[2:3], v[2:3], 0, v[114:115]
	global_load_dwordx4 v[30:33], v[2:3], off
	global_load_dwordx4 v[38:41], v[2:3], off offset:32
	global_load_dwordx4 v[42:45], v[2:3], off offset:64
	global_load_dwordx4 v[46:49], v[2:3], off offset:96
	global_load_dwordx4 v[50:53], v[2:3], off offset:128
	global_load_dwordx4 v[26:29], v[2:3], off offset:160
	global_load_dwordx4 v[22:25], v[2:3], off offset:192
	global_load_dwordx4 v[18:21], v[2:3], off offset:224
	global_load_dwordx4 v[10:13], v[2:3], off offset:256
	global_load_dwordx4 v[14:17], v[2:3], off offset:288
	global_load_dwordx4 v[6:9], v[2:3], off offset:320
	s_nop 0
	global_load_dwordx4 v[2:5], v[2:3], off offset:352
	v_and_b32_e32 v114, 32, v34
	s_add_i32 s7, s7, s6
	s_cmp_lt_i32 s6, 0
	v_lshlrev_b32_e32 v36, 3, v35
	s_cselect_b64 s[10:11], -1, 0
	s_cmp_gt_i32 s6, -1
	s_cselect_b64 s[22:23], -1, 0
	s_waitcnt vmcnt(11)
	v_and_b32_e32 v106, 0xffff0000, v30
	v_lshlrev_b32_e32 v107, 16, v30
	v_mul_f32_e32 v37, v106, v106
	v_lshlrev_b32_e32 v105, 16, v31
	v_fmac_f32_e32 v37, v107, v107
	v_and_b32_e32 v104, 0xffff0000, v31
	v_fmac_f32_e32 v37, v105, v105
	v_lshlrev_b32_e32 v101, 16, v32
	v_fmac_f32_e32 v37, v104, v104
	v_and_b32_e32 v100, 0xffff0000, v32
	v_fmac_f32_e32 v37, v101, v101
	v_lshlrev_b32_e32 v99, 16, v33
	v_fmac_f32_e32 v37, v100, v100
	v_and_b32_e32 v96, 0xffff0000, v33
	v_fmac_f32_e32 v37, v99, v99
	v_fmac_f32_e32 v37, v96, v96
	s_waitcnt vmcnt(10)
	v_lshlrev_b32_e32 v111, 16, v38
	v_and_b32_e32 v110, 0xffff0000, v38
	v_fmac_f32_e32 v37, v111, v111
	v_lshlrev_b32_e32 v109, 16, v39
	v_fmac_f32_e32 v37, v110, v110
	v_and_b32_e32 v108, 0xffff0000, v39
	v_fmac_f32_e32 v37, v109, v109
	v_lshlrev_b32_e32 v102, 16, v40
	v_fmac_f32_e32 v37, v108, v108
	v_and_b32_e32 v97, 0xffff0000, v40
	v_fmac_f32_e32 v37, v102, v102
	v_lshlrev_b32_e32 v91, 16, v41
	v_fmac_f32_e32 v37, v97, v97
	v_and_b32_e32 v90, 0xffff0000, v41
	v_fmac_f32_e32 v37, v91, v91
	v_fmac_f32_e32 v37, v90, v90
	s_waitcnt vmcnt(9)
	v_lshlrev_b32_e32 v103, 16, v42
	v_and_b32_e32 v98, 0xffff0000, v42
	v_fmac_f32_e32 v37, v103, v103
	v_lshlrev_b32_e32 v95, 16, v43
	v_fmac_f32_e32 v37, v98, v98
	v_and_b32_e32 v94, 0xffff0000, v43
	v_fmac_f32_e32 v37, v95, v95
	v_lshlrev_b32_e32 v93, 16, v44
	v_fmac_f32_e32 v37, v94, v94
	v_and_b32_e32 v92, 0xffff0000, v44
	v_fmac_f32_e32 v37, v93, v93
	v_lshlrev_b32_e32 v89, 16, v45
	v_fmac_f32_e32 v37, v92, v92
	v_and_b32_e32 v88, 0xffff0000, v45
	v_fmac_f32_e32 v37, v89, v89
	v_fmac_f32_e32 v37, v88, v88
	s_waitcnt vmcnt(8)
	v_lshlrev_b32_e32 v87, 16, v46
	v_and_b32_e32 v86, 0xffff0000, v46
	v_fmac_f32_e32 v37, v87, v87
	v_lshlrev_b32_e32 v85, 16, v47
	v_fmac_f32_e32 v37, v86, v86
	v_and_b32_e32 v83, 0xffff0000, v47
	v_fmac_f32_e32 v37, v85, v85
	v_lshlrev_b32_e32 v82, 16, v48
	v_fmac_f32_e32 v37, v83, v83
	v_and_b32_e32 v81, 0xffff0000, v48
	v_fmac_f32_e32 v37, v82, v82
	v_lshlrev_b32_e32 v80, 16, v49
	v_fmac_f32_e32 v37, v81, v81
	v_and_b32_e32 v79, 0xffff0000, v49
	v_fmac_f32_e32 v37, v80, v80
	v_fmac_f32_e32 v37, v79, v79
	s_waitcnt vmcnt(7)
	v_lshlrev_b32_e32 v76, 16, v50
	v_and_b32_e32 v71, 0xffff0000, v50
	v_fmac_f32_e32 v37, v76, v76
	v_lshlrev_b32_e32 v70, 16, v51
	v_fmac_f32_e32 v37, v71, v71
	v_and_b32_e32 v69, 0xffff0000, v51
	v_fmac_f32_e32 v37, v70, v70
	v_lshlrev_b32_e32 v68, 16, v52
	v_fmac_f32_e32 v37, v69, v69
	v_and_b32_e32 v67, 0xffff0000, v52
	v_fmac_f32_e32 v37, v68, v68
	v_lshlrev_b32_e32 v66, 16, v53
	v_fmac_f32_e32 v37, v67, v67
	v_and_b32_e32 v65, 0xffff0000, v53
	v_fmac_f32_e32 v37, v66, v66
	v_fmac_f32_e32 v37, v65, v65
	s_waitcnt vmcnt(6)
	v_lshlrev_b32_e32 v64, 16, v26
	v_and_b32_e32 v63, 0xffff0000, v26
	v_fmac_f32_e32 v37, v64, v64
	v_lshlrev_b32_e32 v62, 16, v27
	v_fmac_f32_e32 v37, v63, v63
	v_and_b32_e32 v61, 0xffff0000, v27
	v_fmac_f32_e32 v37, v62, v62
	v_lshlrev_b32_e32 v60, 16, v28
	v_fmac_f32_e32 v37, v61, v61
	v_and_b32_e32 v33, 0xffff0000, v28
	v_fmac_f32_e32 v37, v60, v60
	v_lshlrev_b32_e32 v32, 16, v29
	v_fmac_f32_e32 v37, v33, v33
	v_and_b32_e32 v31, 0xffff0000, v29
	v_fmac_f32_e32 v37, v32, v32
	v_fmac_f32_e32 v37, v31, v31
	s_waitcnt vmcnt(5)
	v_lshlrev_b32_e32 v30, 16, v22
	v_and_b32_e32 v29, 0xffff0000, v22
	v_fmac_f32_e32 v37, v30, v30
	v_lshlrev_b32_e32 v28, 16, v23
	v_fmac_f32_e32 v37, v29, v29
	v_and_b32_e32 v27, 0xffff0000, v23
	v_fmac_f32_e32 v37, v28, v28
	v_lshlrev_b32_e32 v26, 16, v24
	v_fmac_f32_e32 v37, v27, v27
	v_and_b32_e32 v23, 0xffff0000, v24
	v_fmac_f32_e32 v37, v26, v26
	v_lshlrev_b32_e32 v22, 16, v25
	v_fmac_f32_e32 v37, v23, v23
	v_and_b32_e32 v84, 0xffff0000, v25
	v_fmac_f32_e32 v37, v22, v22
	v_fmac_f32_e32 v37, v84, v84
	s_waitcnt vmcnt(4)
	v_lshlrev_b32_e32 v78, 16, v18
	v_and_b32_e32 v77, 0xffff0000, v18
	v_fmac_f32_e32 v37, v78, v78
	v_lshlrev_b32_e32 v75, 16, v19
	v_fmac_f32_e32 v37, v77, v77
	v_and_b32_e32 v74, 0xffff0000, v19
	v_fmac_f32_e32 v37, v75, v75
	v_lshlrev_b32_e32 v73, 16, v20
	v_fmac_f32_e32 v37, v74, v74
	v_and_b32_e32 v72, 0xffff0000, v20
	v_fmac_f32_e32 v37, v73, v73
	v_lshlrev_b32_e32 v25, 16, v21
	v_fmac_f32_e32 v37, v72, v72
	v_and_b32_e32 v24, 0xffff0000, v21
	v_fmac_f32_e32 v37, v25, v25
	v_fmac_f32_e32 v37, v24, v24
	s_waitcnt vmcnt(3)
; __device__ __forceinline__ float bf_lo(unsigned w) { return __uint_as_float(w << 16); }
; __device__ __forceinline__ float bf_hi(unsigned w) { return __uint_as_float(w & 0xffff0000u); }
; __device__ __forceinline__ unsigned cvt_pk_bf16(float lo, float hi) { unsigned r; asm volatile("v_cvt_pk_bf16_f32 %0, %1, %2" : "=v"(r) : "v"(lo), "v"(hi)); return r; }
; __device__ __forceinline__ void attn_unit_dma(const bf16_t* __restrict__ Qb, const bf16_t* __restrict__ Kh, const bf16_t* __restrict__ Vh, int seq, char* lds, LAS unsigned char* ldsl, ...
;     ...
;     { auto rr_ = __builtin_amdgcn_permlane32_swap(__float_as_uint(ss), __float_as_uint(ss), false, false); ss = __uint_as_float(rr_[0]) + __uint_as_float(rr_[1]); }
;     const float rstd = rsqrtf(ss * (1.0f / DQK) + EPS) * (SCALE * 1.4426950408889634f);
; #pragma unroll
;     for (int d0 = 0; d0 < 8; ++d0) { const u32x4 w = *reinterpret_cast<const u32x4*>(&qr[d0]); float f[8]; f[0] = bf_lo(w.x); f[1] = bf_hi(w.x); f[2] = bf_lo(w.y); f[3] = bf_hi(w.y); f[4] = bf_lo(w.z); f[5] = bf_hi(w.z); f[6] = bf_lo(w.w); f[7] = bf_hi(w.w);
;       const f32x4 g0 = *(const f32x4*)(gq + d0 * 16 + hi * 8), g1 = *(const f32x4*)(gq + d0 * 16 + hi * 8 + 4);
;       u32x4 o; o.x = cvt_pk_bf16(f[0] * rstd * g0[0], f[1] * rstd * g0[1]); o.y = cvt_pk_bf16(f[2] * rstd * g0[2], f[3] * rstd * g0[3]); o.z = cvt_pk_bf16(f[4] * rstd * g1[0], f[5] * rstd * g1[1]); o.w = cvt_pk_bf16(f[6] * rstd * g1[2], f[7] * rstd * g1[3]);
;       qr[d0] = *reinterpret_cast<const bf16x8*>(&o); }
	v_lshlrev_b32_e32 v46, 16, v10
	v_and_b32_e32 v47, 0xffff0000, v10
	v_fmac_f32_e32 v37, v46, v46
	v_lshlrev_b32_e32 v49, 16, v11
	v_fmac_f32_e32 v37, v47, v47
	v_and_b32_e32 v51, 0xffff0000, v11
	v_fmac_f32_e32 v37, v49, v49
	v_lshlrev_b32_e32 v53, 16, v12
	v_fmac_f32_e32 v37, v51, v51
	v_and_b32_e32 v55, 0xffff0000, v12
	v_fmac_f32_e32 v37, v53, v53
	v_lshlrev_b32_e32 v57, 16, v13
	v_fmac_f32_e32 v37, v55, v55
	v_and_b32_e32 v21, 0xffff0000, v13
	s_waitcnt vmcnt(2)
	v_and_b32_e32 v20, 0xffff0000, v17
	v_fmac_f32_e32 v37, v57, v57
	v_pk_mul_f32 v[10:11], v[20:21], v[20:21]
	v_lshlrev_b32_e32 v48, 16, v14
	v_add_f32_e32 v11, v11, v37
	v_and_b32_e32 v50, 0xffff0000, v14
	v_fmac_f32_e32 v11, v48, v48
	v_lshlrev_b32_e32 v52, 16, v15
	v_fmac_f32_e32 v11, v50, v50
	v_and_b32_e32 v54, 0xffff0000, v15
	v_fmac_f32_e32 v11, v52, v52
	v_lshlrev_b32_e32 v56, 16, v16
	v_fmac_f32_e32 v11, v54, v54
	v_and_b32_e32 v58, 0xffff0000, v16
	v_fmac_f32_e32 v11, v56, v56
	v_lshlrev_b32_e32 v59, 16, v17
	v_fmac_f32_e32 v11, v58, v58
	v_fmac_f32_e32 v11, v59, v59
	v_add_f32_e32 v12, v10, v11
	s_waitcnt vmcnt(1)
	v_lshlrev_b32_e32 v37, 16, v6
	v_and_b32_e32 v38, 0xffff0000, v6
	v_fmac_f32_e32 v12, v37, v37
	v_lshlrev_b32_e32 v39, 16, v7
	v_fmac_f32_e32 v12, v38, v38
	v_and_b32_e32 v40, 0xffff0000, v7
	v_fmac_f32_e32 v12, v39, v39
	v_lshlrev_b32_e32 v41, 16, v8
	v_fmac_f32_e32 v12, v40, v40
	v_and_b32_e32 v43, 0xffff0000, v8
	v_fmac_f32_e32 v12, v41, v41
	v_lshlrev_b32_e32 v45, 16, v9
	v_fmac_f32_e32 v12, v43, v43
	v_fmac_f32_e32 v12, v45, v45
	v_and_b32_e32 v11, 0xffff0000, v9
	s_waitcnt vmcnt(0)
	v_lshlrev_b32_e32 v42, 16, v2
	v_fmac_f32_e32 v12, v11, v11
	v_and_b32_e32 v44, 0xffff0000, v2
	v_fmac_f32_e32 v12, v42, v42
	v_and_b32_e32 v14, 0xffff0000, v3
	v_lshlrev_b32_e32 v15, 16, v3
	v_fmac_f32_e32 v12, v44, v44
	v_pk_mul_f32 v[2:3], v[14:15], v[14:15]
	v_and_b32_e32 v18, 0xffff0000, v4
	v_add_f32_e32 v3, v3, v12
	v_lshlrev_b32_e32 v19, 16, v4
	v_lshlrev_b32_e32 v17, 16, v5
	v_and_b32_e32 v10, 0xffff0000, v5
	v_add_f32_e32 v5, v2, v3
	v_pk_mul_f32 v[2:3], v[18:19], v[18:19]
	v_mov_b32_e32 v16, v10
	v_add_f32_e32 v3, v3, v5
	v_add_f32_e32 v4, v2, v3
	v_pk_mul_f32 v[2:3], v[16:17], v[16:17]
	s_nop 0
	v_add_f32_e32 v3, v3, v4
	v_add_f32_e32 v2, v2, v3
	v_mov_b32_e32 v3, v2
	s_nop 1
	v_permlane32_swap_b32_e32 v2, v3
	v_add_f32_e32 v2, v2, v3
	v_fmamk_f32 v2, v2, 0x3baaaaab, v198
	v_cmp_gt_f32_e32 vcc, s89, v2
	v_mul_f32_e32 v3, 0x4b800000, v2
	s_nop 0
	v_cndmask_b32_e32 v2, v2, v3, vcc
	v_rsq_f32_e32 v2, v2
	s_nop 0
	v_mul_f32_e32 v3, 0x45800000, v2
	v_cndmask_b32_e32 v2, v2, v3, vcc
	v_mul_f32_e32 v12, 0x3dd53b94, v2
	global_load_dwordx4 v[172:175], v114, s[14:15] offset:16
	global_load_dwordx4 v[176:179], v114, s[14:15]
	global_load_dwordx4 v[220:223], v114, s[14:15] offset:80
	global_load_dwordx4 v[224:227], v114, s[14:15] offset:64
	global_load_dwordx4 v[228:231], v114, s[14:15] offset:144
	global_load_dwordx4 v[232:235], v114, s[14:15] offset:128
	global_load_dwordx4 v[236:239], v114, s[14:15] offset:208
	global_load_dwordx4 v[240:243], v114, s[14:15] offset:192
	global_load_dwordx4 v[200:203], v114, s[14:15] offset:272
	global_load_dwordx4 v[204:207], v114, s[14:15] offset:256
	global_load_dwordx4 v[208:211], v114, s[14:15] offset:336
	global_load_dwordx4 v[246:249], v114, s[14:15] offset:320
	v_mul_f32_e32 v13, v12, v107
	s_and_b64 vcc, exec, s[10:11]
	s_waitcnt vmcnt(10)
	v_mov_b32_e32 v2, v172
	v_mov_b32_e32 v3, v173
	v_mov_b32_e32 v4, v174
	v_mov_b32_e32 v5, v175
	v_mov_b32_e32 v6, v176
	v_mov_b32_e32 v7, v177
	v_mov_b32_e32 v8, v178
	v_mov_b32_e32 v9, v179
	global_load_dwordx4 v[172:175], v114, s[14:15] offset:400
	global_load_dwordx4 v[176:179], v114, s[14:15] offset:384
	v_mul_f32_e32 v6, v6, v13
	v_mul_f32_e32 v13, v12, v106
	v_mul_f32_e32 v7, v7, v13
	v_cvt_pk_bf16_f32 v116, v6, v7
	v_mul_f32_e32 v6, v12, v105
	v_mul_f32_e32 v6, v8, v6
	v_mul_f32_e32 v7, v12, v104
	v_mul_f32_e32 v7, v9, v7
	v_cvt_pk_bf16_f32 v117, v6, v7
	v_mul_f32_e32 v6, v12, v101
	v_mul_f32_e32 v2, v2, v6
	v_mul_f32_e32 v6, v12, v100
	v_mul_f32_e32 v3, v3, v6
	v_cvt_pk_bf16_f32 v118, v2, v3
	v_mul_f32_e32 v2, v12, v99
	v_mul_f32_e32 v3, v12, v96
	v_mul_f32_e32 v2, v4, v2
	v_mul_f32_e32 v3, v5, v3
	v_cvt_pk_bf16_f32 v119, v2, v3
	v_mul_f32_e32 v13, v12, v111
	s_waitcnt vmcnt(10)
	v_mov_b32_e32 v2, v220
	v_mov_b32_e32 v3, v221
	v_mov_b32_e32 v4, v222
	v_mov_b32_e32 v5, v223
	v_mov_b32_e32 v6, v224
	v_mov_b32_e32 v7, v225
	v_mov_b32_e32 v8, v226
	v_mov_b32_e32 v9, v227
	global_load_dwordx4 v[220:223], v114, s[14:15] offset:464
	global_load_dwordx4 v[224:227], v114, s[14:15] offset:448
	v_mul_f32_e32 v6, v6, v13
	v_mul_f32_e32 v13, v12, v110
	v_mul_f32_e32 v7, v7, v13
	v_cvt_pk_bf16_f32 v120, v6, v7
	v_mul_f32_e32 v6, v12, v109
	v_mul_f32_e32 v6, v8, v6
	v_mul_f32_e32 v7, v12, v108
	v_mul_f32_e32 v7, v9, v7
	v_cvt_pk_bf16_f32 v121, v6, v7
	v_mul_f32_e32 v6, v12, v102
	v_mul_f32_e32 v2, v2, v6
	v_mul_f32_e32 v6, v12, v97
	v_mul_f32_e32 v3, v3, v6
	v_cvt_pk_bf16_f32 v122, v2, v3
	v_mul_f32_e32 v2, v12, v91
	v_mul_f32_e32 v3, v12, v90
	v_mul_f32_e32 v2, v4, v2
	v_mul_f32_e32 v3, v5, v3
	v_cvt_pk_bf16_f32 v123, v2, v3
	v_mul_f32_e32 v13, v12, v103
	s_waitcnt vmcnt(10)
; __device__ __forceinline__ float bf_lo(unsigned w) { return __uint_as_float(w << 16); }
; __device__ __forceinline__ float bf_hi(unsigned w) { return __uint_as_float(w & 0xffff0000u); }
; __device__ __forceinline__ unsigned cvt_pk_bf16(float lo, float hi) { unsigned r; asm volatile("v_cvt_pk_bf16_f32 %0, %1, %2" : "=v"(r) : "v"(lo), "v"(hi)); return r; }
; __device__ __forceinline__ void attn_unit_dma(const bf16_t* __restrict__ Qb, const bf16_t* __restrict__ Kh, const bf16_t* __restrict__ Vh, int seq, char* lds, LAS unsigned char* ldsl, ...
;     ...
;     const float rstd = rsqrtf(ss * (1.0f / DQK) + EPS) * (SCALE * 1.4426950408889634f);
; #pragma unroll
;     for (int d0 = 0; d0 < 8; ++d0) { const u32x4 w = *reinterpret_cast<const u32x4*>(&qr[d0]); float f[8]; f[0] = bf_lo(w.x); f[1] = bf_hi(w.x); f[2] = bf_lo(w.y); f[3] = bf_hi(w.y); f[4] = bf_lo(w.z); f[5] = bf_hi(w.z); f[6] = bf_lo(w.w); f[7] = bf_hi(w.w);
;       const f32x4 g0 = *(const f32x4*)(gq + d0 * 16 + hi * 8), g1 = *(const f32x4*)(gq + d0 * 16 + hi * 8 + 4);
;       u32x4 o; o.x = cvt_pk_bf16(f[0] * rstd * g0[0], f[1] * rstd * g0[1]); o.y = cvt_pk_bf16(f[2] * rstd * g0[2], f[3] * rstd * g0[3]); o.z = cvt_pk_bf16(f[4] * rstd * g1[0], f[5] * rstd * g1[1]); o.w = cvt_pk_bf16(f[6] * rstd * g1[2], f[7] * rstd * g1[3]);
;       qr[d0] = *reinterpret_cast<const bf16x8*>(&o); }
;     const int t = tok0 + wid * QBLK + r32;
; #pragma unroll
;     for (int ax = 0; ax < 2; ++ax) {
;       const int pos = tok0 < 0 ? 0 : (ax == 0 ? (t >> 6) : (t & 63));
;       const u32x4 w1 = *reinterpret_cast<const u32x4*>(&qr[8 + 2 * ax]), w2 = *reinterpret_cast<const u32x4*>(&qr[9 + 2 * ax]);
;       float x1[8], x2[8]; x1[0] = bf_lo(w1.x); x1[1] = bf_hi(w1.x); x1[2] = bf_lo(w1.y); x1[3] = bf_hi(w1.y); x1[4] = bf_lo(w1.z); x1[5] = bf_hi(w1.z); x1[6] = bf_lo(w1.w); x1[7] = bf_hi(w1.w);
;       x2[0] = bf_lo(w2.x); x2[1] = bf_hi(w2.x); x2[2] = bf_lo(w2.y); x2[3] = bf_hi(w2.y); x2[4] = bf_lo(w2.z); x2[5] = bf_hi(w2.z); x2[6] = bf_lo(w2.w); x2[7] = bf_hi(w2.w);
;       float o1[8], o2[8];
; #pragma unroll
;       for (int e = 0; e < 8; ++e) { const f32x2 cs = tok0 < 0 ? (f32x2){1.f, 0.f} : *(const f32x2*)(rope + ((size_t)pos * 16 + hi * 8 + e) * 2);
	v_mov_b32_e32 v2, v228
	v_mov_b32_e32 v3, v229
	v_mov_b32_e32 v4, v230
	v_mov_b32_e32 v5, v231
	v_mov_b32_e32 v6, v232
	v_mov_b32_e32 v7, v233
	v_mov_b32_e32 v8, v234
	v_mov_b32_e32 v9, v235
	v_mul_f32_e32 v6, v13, v6
	v_mul_f32_e32 v13, v12, v98
	v_mul_f32_e32 v7, v13, v7
	v_cvt_pk_bf16_f32 v124, v6, v7
	v_mul_f32_e32 v6, v12, v95
	v_mul_f32_e32 v6, v6, v8
	v_mul_f32_e32 v7, v12, v94
	v_mul_f32_e32 v7, v7, v9
	v_cvt_pk_bf16_f32 v125, v6, v7
	v_mul_f32_e32 v6, v12, v93
	v_mul_f32_e32 v2, v6, v2
	v_mul_f32_e32 v6, v12, v92
	v_mul_f32_e32 v3, v6, v3
	v_cvt_pk_bf16_f32 v126, v2, v3
	v_mul_f32_e32 v2, v12, v89
	v_mul_f32_e32 v3, v12, v88
	v_mul_f32_e32 v2, v2, v4
	v_mul_f32_e32 v3, v3, v5
	v_cvt_pk_bf16_f32 v127, v2, v3
	v_mul_f32_e32 v13, v12, v87
	s_waitcnt vmcnt(8)
	v_mov_b32_e32 v2, v236
	v_mov_b32_e32 v3, v237
	v_mov_b32_e32 v4, v238
	v_mov_b32_e32 v5, v239
	v_mov_b32_e32 v6, v240
	v_mov_b32_e32 v7, v241
	v_mov_b32_e32 v8, v242
	v_mov_b32_e32 v9, v243
	v_mul_f32_e32 v6, v13, v6
	v_mul_f32_e32 v13, v12, v86
	v_mul_f32_e32 v7, v13, v7
	v_cvt_pk_bf16_f32 v128, v6, v7
	v_mul_f32_e32 v6, v12, v85
	v_mul_f32_e32 v6, v6, v8
	v_mul_f32_e32 v7, v12, v83
	v_mul_f32_e32 v7, v7, v9
	v_cvt_pk_bf16_f32 v129, v6, v7
	v_mul_f32_e32 v6, v12, v82
	v_mul_f32_e32 v2, v6, v2
	v_mul_f32_e32 v6, v12, v81
	v_mul_f32_e32 v3, v6, v3
	v_cvt_pk_bf16_f32 v130, v2, v3
	v_mul_f32_e32 v2, v12, v80
	v_mul_f32_e32 v3, v12, v79
	v_mul_f32_e32 v2, v2, v4
	v_mul_f32_e32 v3, v3, v5
	v_cvt_pk_bf16_f32 v131, v2, v3
	v_mul_f32_e32 v13, v12, v76
	s_waitcnt vmcnt(6)
	v_mov_b32_e32 v2, v200
	v_mov_b32_e32 v3, v201
	v_mov_b32_e32 v4, v202
	v_mov_b32_e32 v5, v203
	v_mov_b32_e32 v6, v204
	v_mov_b32_e32 v7, v205
	v_mov_b32_e32 v8, v206
	v_mov_b32_e32 v9, v207
	v_mul_f32_e32 v6, v13, v6
	v_mul_f32_e32 v13, v12, v71
	v_mul_f32_e32 v7, v13, v7
	v_cvt_pk_bf16_f32 v132, v6, v7
	v_mul_f32_e32 v6, v12, v70
	v_mul_f32_e32 v6, v6, v8
	v_mul_f32_e32 v7, v12, v69
	v_mul_f32_e32 v7, v7, v9
	v_cvt_pk_bf16_f32 v133, v6, v7
	v_mul_f32_e32 v6, v12, v68
	v_mul_f32_e32 v2, v6, v2
	v_mul_f32_e32 v6, v12, v67
	v_mul_f32_e32 v3, v6, v3
	v_cvt_pk_bf16_f32 v134, v2, v3
	v_mul_f32_e32 v2, v12, v66
	v_mul_f32_e32 v3, v12, v65
	v_mul_f32_e32 v2, v2, v4
	v_mul_f32_e32 v3, v3, v5
	v_cvt_pk_bf16_f32 v135, v2, v3
	v_mul_f32_e32 v13, v12, v64
	s_waitcnt vmcnt(4)
	v_mov_b32_e32 v2, v208
	v_mov_b32_e32 v3, v209
	v_mov_b32_e32 v4, v210
	v_mov_b32_e32 v5, v211
	v_mov_b32_e32 v6, v246
	v_mov_b32_e32 v7, v247
	v_mov_b32_e32 v8, v248
	v_mov_b32_e32 v9, v249
	v_mul_f32_e32 v6, v13, v6
	v_mul_f32_e32 v13, v12, v63
	v_mul_f32_e32 v7, v13, v7
	v_cvt_pk_bf16_f32 v136, v6, v7
	v_mul_f32_e32 v6, v12, v62
	v_mul_f32_e32 v6, v6, v8
	v_mul_f32_e32 v7, v12, v61
	v_mul_f32_e32 v7, v7, v9
	v_cvt_pk_bf16_f32 v137, v6, v7
	v_mul_f32_e32 v6, v12, v60
	v_mul_f32_e32 v2, v6, v2
	v_mul_f32_e32 v6, v12, v33
	v_mul_f32_e32 v3, v6, v3
	v_cvt_pk_bf16_f32 v138, v2, v3
	v_mul_f32_e32 v2, v12, v32
	v_mul_f32_e32 v3, v12, v31
	v_mul_f32_e32 v2, v2, v4
	v_mul_f32_e32 v3, v3, v5
	v_cvt_pk_bf16_f32 v139, v2, v3
	v_mul_f32_e32 v13, v12, v30
	s_waitcnt vmcnt(2)
	v_mov_b32_e32 v2, v172
	v_mov_b32_e32 v3, v173
	v_mov_b32_e32 v4, v174
	v_mov_b32_e32 v5, v175
	v_mov_b32_e32 v6, v176
	v_mov_b32_e32 v7, v177
	v_mov_b32_e32 v8, v178
	v_mov_b32_e32 v9, v179
	v_mul_f32_e32 v6, v13, v6
	v_mul_f32_e32 v13, v12, v29
	v_mul_f32_e32 v7, v13, v7
	v_cvt_pk_bf16_f32 v140, v6, v7
	v_mul_f32_e32 v6, v12, v28
	v_mul_f32_e32 v6, v6, v8
	v_mul_f32_e32 v7, v12, v27
	v_mul_f32_e32 v7, v7, v9
	v_cvt_pk_bf16_f32 v141, v6, v7
	v_mul_f32_e32 v6, v12, v26
	v_mul_f32_e32 v2, v6, v2
	v_mul_f32_e32 v6, v12, v23
	v_mul_f32_e32 v3, v6, v3
	v_cvt_pk_bf16_f32 v142, v2, v3
	v_mul_f32_e32 v2, v12, v22
	v_mul_f32_e32 v3, v12, v84
	v_mul_f32_e32 v2, v2, v4
	v_mul_f32_e32 v3, v3, v5
	v_cvt_pk_bf16_f32 v143, v2, v3
	v_mul_f32_e32 v13, v12, v78
	s_waitcnt vmcnt(0)
	v_mov_b32_e32 v2, v220
	v_mov_b32_e32 v3, v221
	v_mov_b32_e32 v4, v222
	v_mov_b32_e32 v5, v223
	v_mov_b32_e32 v6, v224
	v_mov_b32_e32 v7, v225
	v_mov_b32_e32 v8, v226
	v_mov_b32_e32 v9, v227
	v_mul_f32_e32 v6, v13, v6
	v_mul_f32_e32 v13, v12, v77
	v_mul_f32_e32 v7, v13, v7
	v_cvt_pk_bf16_f32 v144, v6, v7
	v_mul_f32_e32 v6, v12, v75
	v_mul_f32_e32 v6, v6, v8
	v_mul_f32_e32 v7, v12, v74
	v_mul_f32_e32 v7, v7, v9
	v_cvt_pk_bf16_f32 v145, v6, v7
	v_mul_f32_e32 v6, v12, v73
	v_mul_f32_e32 v2, v6, v2
	v_mul_f32_e32 v6, v12, v72
	v_mul_f32_e32 v3, v6, v3
	v_cvt_pk_bf16_f32 v146, v2, v3
	v_mul_f32_e32 v2, v12, v25
	v_mul_f32_e32 v2, v2, v4
	v_mul_f32_e32 v3, v12, v24
	v_add_u32_e32 v13, s7, v180
	v_mul_f32_e32 v3, v3, v5
	v_cvt_pk_bf16_f32 v147, v2, v3
	v_ashrrev_i32_e32 v2, 6, v13
	v_ashrrev_i32_e32 v3, 31, v2
	v_lshlrev_b64 v[4:5], 4, v[2:3]
	v_mov_b32_e32 v7, 0
	v_mov_b32_e32 v6, 1.0
	v_or_b32_e32 v4, v4, v36
	v_mov_b32_e32 v8, 1.0
	v_mov_b32_e32 v9, 0
	s_cbranch_vccnz .LBB0_821
	v_lshl_add_u64 v[2:3], v[4:5], 3, s[18:19]
	global_load_dwordx2 v[8:9], v[2:3], off
